# final norm output stores write-through (sc1) with the pipelined loop
# speedup vs baseline: 1.0036x; 1.0020x over previous
.Lfn_loop:
	s_waitcnt vmcnt(8)
	v_lshlrev_b32_e32 v100, 16, v80
	v_and_b32_e32 v101, 0xffff0000, v80
	v_lshlrev_b32_e32 v102, 16, v81
	v_and_b32_e32 v103, 0xffff0000, v81
	v_lshlrev_b32_e32 v104, 16, v82
	v_and_b32_e32 v105, 0xffff0000, v82
	v_lshlrev_b32_e32 v106, 16, v83
	v_and_b32_e32 v107, 0xffff0000, v83
	v_lshlrev_b32_e32 v108, 16, v84
	v_and_b32_e32 v109, 0xffff0000, v84
	v_lshlrev_b32_e32 v110, 16, v85
	v_and_b32_e32 v111, 0xffff0000, v85
	v_lshlrev_b32_e32 v112, 16, v86
	v_and_b32_e32 v113, 0xffff0000, v86
	v_lshlrev_b32_e32 v114, 16, v87
	v_and_b32_e32 v115, 0xffff0000, v87
	v_mul_f32_e32 v116, v101, v101
	v_mul_f32_e32 v117, v105, v105
	v_mul_f32_e32 v118, v109, v109
	v_mul_f32_e32 v119, v113, v113
	v_fmac_f32_e32 v116, v100, v100
	v_fmac_f32_e32 v117, v104, v104
	v_fmac_f32_e32 v118, v108, v108
	v_fmac_f32_e32 v119, v112, v112
	v_fmac_f32_e32 v116, v102, v102
	v_fmac_f32_e32 v117, v106, v106
	v_fmac_f32_e32 v118, v110, v110
	v_fmac_f32_e32 v119, v114, v114
	v_fmac_f32_e32 v116, v103, v103
	v_fmac_f32_e32 v117, v107, v107
	v_fmac_f32_e32 v118, v111, v111
	v_fmac_f32_e32 v119, v115, v115
	v_add_f32_e32 v15, v116, v117
	v_add_f32_e32 v15, v15, v118
	v_add_f32_e32 v15, v15, v119
	ds_bpermute_b32 v36, v8, v15
	s_waitcnt lgkmcnt(0)
	v_add_f32_e32 v15, v15, v36
	ds_bpermute_b32 v36, v9, v15
	s_waitcnt lgkmcnt(0)
	v_add_f32_e32 v15, v15, v36
	ds_bpermute_b32 v36, v10, v15
	s_waitcnt lgkmcnt(0)
	v_add_f32_e32 v15, v15, v36
	ds_bpermute_b32 v36, v11, v15
	s_waitcnt lgkmcnt(0)
	v_add_f32_e32 v15, v15, v36
	ds_bpermute_b32 v36, v12, v15
	s_waitcnt lgkmcnt(0)
	v_add_f32_e32 v15, v15, v36
	ds_bpermute_b32 v36, v13, v15
	s_waitcnt lgkmcnt(0)
	v_add_f32_e32 v15, v15, v36
	v_fmamk_f32 v15, v15, 0x3a800000, v14
	v_mul_f32_e32 v36, 0x4b800000, v15
	v_cmp_gt_f32_e32 vcc, s22, v15
	s_lshl_b32 s20, s11, 12
	s_add_u32 s20, s4, s20
	v_cndmask_b32_e32 v15, v15, v36, vcc
	v_rsq_f32_e32 v15, v15
	s_addc_u32 s21, s5, 0
	s_nop 0
	v_mul_f32_e32 v37, 0x45800000, v15
	v_cndmask_b32_e32 v38, v15, v37, vcc
	v_pk_mul_f32 v[40:41], v[38:39], v[100:101] op_sel_hi:[0,1]
	v_pk_mul_f32 v[42:43], v[38:39], v[102:103] op_sel_hi:[0,1]
	v_pk_mul_f32 v[44:45], v[60:61], v[40:41]
	v_pk_mul_f32 v[46:47], v[62:63], v[42:43]
	global_store_dwordx4 v4, v[44:47], s[20:21] sc1
	v_pk_mul_f32 v[40:41], v[38:39], v[104:105] op_sel_hi:[0,1]
	v_pk_mul_f32 v[42:43], v[38:39], v[106:107] op_sel_hi:[0,1]
	v_pk_mul_f32 v[44:45], v[64:65], v[40:41]
	v_pk_mul_f32 v[46:47], v[66:67], v[42:43]
	global_store_dwordx4 v4, v[44:47], s[20:21] offset:1024 sc1
	v_pk_mul_f32 v[40:41], v[38:39], v[108:109] op_sel_hi:[0,1]
	v_pk_mul_f32 v[42:43], v[38:39], v[110:111] op_sel_hi:[0,1]
	v_pk_mul_f32 v[44:45], v[68:69], v[40:41]
	v_pk_mul_f32 v[46:47], v[70:71], v[42:43]
	global_store_dwordx4 v4, v[44:47], s[20:21] offset:2048 sc1
	v_pk_mul_f32 v[40:41], v[38:39], v[112:113] op_sel_hi:[0,1]
	v_pk_mul_f32 v[42:43], v[38:39], v[114:115] op_sel_hi:[0,1]
	v_pk_mul_f32 v[44:45], v[72:73], v[40:41]
	v_pk_mul_f32 v[46:47], v[74:75], v[42:43]
	global_store_dwordx4 v4, v[44:47], s[20:21] offset:3072 sc1
	s_add_i32 s11, s11, s12
	s_add_i32 s11, s11, s12
	s_min_i32 s14, s11, 0x3fff
	s_lshl_b32 s16, s14, 11
	s_add_u32 s16, s6, s16
	s_addc_u32 s17, s7, 0
	global_load_dwordx2 v[80:81], v3, s[16:17]
	global_load_dwordx2 v[82:83], v3, s[16:17] offset:512
	global_load_dwordx2 v[84:85], v3, s[16:17] offset:1024
	global_load_dwordx2 v[86:87], v3, s[16:17] offset:1536
	s_waitcnt vmcnt(8)
	s_cmp_gt_i32 s13, 0x3fff
	s_cbranch_scc1 .Lfn_end
	v_lshlrev_b32_e32 v100, 16, v88
	v_and_b32_e32 v101, 0xffff0000, v88
	v_lshlrev_b32_e32 v102, 16, v89
	v_and_b32_e32 v103, 0xffff0000, v89
	v_lshlrev_b32_e32 v104, 16, v90
	v_and_b32_e32 v105, 0xffff0000, v90
	v_lshlrev_b32_e32 v106, 16, v91
	v_and_b32_e32 v107, 0xffff0000, v91
	v_lshlrev_b32_e32 v108, 16, v92
	v_and_b32_e32 v109, 0xffff0000, v92
	v_lshlrev_b32_e32 v110, 16, v93
	v_and_b32_e32 v111, 0xffff0000, v93
	v_lshlrev_b32_e32 v112, 16, v94
	v_and_b32_e32 v113, 0xffff0000, v94
	v_lshlrev_b32_e32 v114, 16, v95
	v_and_b32_e32 v115, 0xffff0000, v95
	v_mul_f32_e32 v116, v101, v101
	v_mul_f32_e32 v117, v105, v105
	v_mul_f32_e32 v118, v109, v109
	v_mul_f32_e32 v119, v113, v113
	v_fmac_f32_e32 v116, v100, v100
	v_fmac_f32_e32 v117, v104, v104
	v_fmac_f32_e32 v118, v108, v108
	v_fmac_f32_e32 v119, v112, v112
	v_fmac_f32_e32 v116, v102, v102
	v_fmac_f32_e32 v117, v106, v106
	v_fmac_f32_e32 v118, v110, v110
	v_fmac_f32_e32 v119, v114, v114
	v_fmac_f32_e32 v116, v103, v103
	v_fmac_f32_e32 v117, v107, v107
	v_fmac_f32_e32 v118, v111, v111
	v_fmac_f32_e32 v119, v115, v115
	v_add_f32_e32 v15, v116, v117
	v_add_f32_e32 v15, v15, v118
	v_add_f32_e32 v15, v15, v119
	ds_bpermute_b32 v36, v8, v15
	s_waitcnt lgkmcnt(0)
	v_add_f32_e32 v15, v15, v36
	ds_bpermute_b32 v36, v9, v15
	s_waitcnt lgkmcnt(0)
	v_add_f32_e32 v15, v15, v36
	ds_bpermute_b32 v36, v10, v15
	s_waitcnt lgkmcnt(0)
	v_add_f32_e32 v15, v15, v36
	ds_bpermute_b32 v36, v11, v15
	s_waitcnt lgkmcnt(0)
	v_add_f32_e32 v15, v15, v36
	ds_bpermute_b32 v36, v12, v15
	s_waitcnt lgkmcnt(0)
	v_add_f32_e32 v15, v15, v36
	ds_bpermute_b32 v36, v13, v15
	s_waitcnt lgkmcnt(0)
	v_add_f32_e32 v15, v15, v36
	v_fmamk_f32 v15, v15, 0x3a800000, v14
	v_mul_f32_e32 v36, 0x4b800000, v15
	v_cmp_gt_f32_e32 vcc, s22, v15
	s_lshl_b32 s20, s13, 12
	s_add_u32 s20, s4, s20
	v_cndmask_b32_e32 v15, v15, v36, vcc
	v_rsq_f32_e32 v15, v15
	s_addc_u32 s21, s5, 0
	s_nop 0
	v_mul_f32_e32 v37, 0x45800000, v15
	v_cndmask_b32_e32 v38, v15, v37, vcc
	v_pk_mul_f32 v[40:41], v[38:39], v[100:101] op_sel_hi:[0,1]
	v_pk_mul_f32 v[42:43], v[38:39], v[102:103] op_sel_hi:[0,1]
	v_pk_mul_f32 v[44:45], v[60:61], v[40:41]
	v_pk_mul_f32 v[46:47], v[62:63], v[42:43]
	global_store_dwordx4 v4, v[44:47], s[20:21] sc1
	v_pk_mul_f32 v[40:41], v[38:39], v[104:105] op_sel_hi:[0,1]
	v_pk_mul_f32 v[42:43], v[38:39], v[106:107] op_sel_hi:[0,1]
	v_pk_mul_f32 v[44:45], v[64:65], v[40:41]
	v_pk_mul_f32 v[46:47], v[66:67], v[42:43]
	global_store_dwordx4 v4, v[44:47], s[20:21] offset:1024 sc1
	v_pk_mul_f32 v[40:41], v[38:39], v[108:109] op_sel_hi:[0,1]
	v_pk_mul_f32 v[42:43], v[38:39], v[110:111] op_sel_hi:[0,1]
	v_pk_mul_f32 v[44:45], v[68:69], v[40:41]
	v_pk_mul_f32 v[46:47], v[70:71], v[42:43]
	global_store_dwordx4 v4, v[44:47], s[20:21] offset:2048 sc1
	v_pk_mul_f32 v[40:41], v[38:39], v[112:113] op_sel_hi:[0,1]
	v_pk_mul_f32 v[42:43], v[38:39], v[114:115] op_sel_hi:[0,1]
	v_pk_mul_f32 v[44:45], v[72:73], v[40:41]
	v_pk_mul_f32 v[46:47], v[74:75], v[42:43]
	global_store_dwordx4 v4, v[44:47], s[20:21] offset:3072 sc1
	s_add_i32 s13, s13, s12
	s_add_i32 s13, s13, s12
	s_min_i32 s14, s13, 0x3fff
	s_lshl_b32 s18, s14, 11
	s_add_u32 s18, s6, s18
	s_addc_u32 s19, s7, 0
	global_load_dwordx2 v[88:89], v3, s[18:19]
	global_load_dwordx2 v[90:91], v3, s[18:19] offset:512
	global_load_dwordx2 v[92:93], v3, s[18:19] offset:1024
	global_load_dwordx2 v[94:95], v3, s[18:19] offset:1536
	s_cmp_le_i32 s11, 0x3fff
	s_cbranch_scc1 .Lfn_loop
